# v3 + qkt K-fragment LDS reads software-pipelined over dead register quads + S4 rebalance step 2
# speedup vs baseline: 1.0196x; 1.0031x over previous
.LBB0_852:
	s_and_b64 s[14:15], s[70:71], exec
	s_cselect_b32 s24, 2, 4
	s_cmpk_lt_i32 s31, 0xf0
	s_cselect_b32 s25, 6, 5
	s_cselect_b32 s29, 8, 9
	s_lshl_b64 s[14:15], s[88:89], 8
	s_add_u32 s14, s59, s14
	s_addc_u32 s15, s18, s15
	s_add_i32 s0, s0, s5
	v_mbcnt_lo_u32_b32 v4, -1, 0
	v_mbcnt_hi_u32_b32 v4, -1, v4
	v_readlane_b32 s5, v254, 7
	v_and_or_b32 v130, v4, 31, s58
	v_ashrrev_i32_e32 v2, 2, v4
	v_lshlrev_b64 v[0:1], 8, v[130:131]
	v_and_b32_e32 v2, -8, v2
	v_add_u32_e32 v10, s5, v4
	s_max_i32 s0, s0, 0
	v_ashrrev_i32_e32 v3, 31, v2
	v_lshl_add_u64 v[0:1], s[14:15], 0, v[0:1]
	v_ashrrev_i32_e32 v11, 4, v10
	v_lshl_add_u64 v[0:1], v[2:3], 1, v[0:1]
	v_add_u32_e32 v2, s0, v11
	v_ashrrev_i32_e32 v3, 31, v2
	v_lshlrev_b32_e32 v12, 4, v4
	v_lshlrev_b64 v[2:3], 8, v[2:3]
	s_mov_b64 s[14:15], 0x2000
	global_load_dwordx4 v[160:163], v[0:1], off
	global_load_dwordx4 v[156:159], v[0:1], off offset:32
	global_load_dwordx4 v[152:155], v[0:1], off offset:64
	global_load_dwordx4 v[148:151], v[0:1], off offset:96
	global_load_dwordx4 v[144:147], v[0:1], off offset:128
	global_load_dwordx4 v[136:139], v[0:1], off offset:160
	v_and_b32_e32 v130, 0xf0, v12
	v_lshl_add_u64 v[4:5], v[2:3], 0, s[14:15]
	v_lshl_add_u64 v[6:7], s[46:47], 0, v[2:3]
	v_lshl_add_u64 v[6:7], v[6:7], 0, v[130:131]
	v_lshl_add_u64 v[8:9], s[46:47], 0, v[4:5]
	v_lshl_add_u64 v[8:9], v[8:9], 0, v[130:131]
	global_load_dwordx4 v[120:123], v[6:7], off
	global_load_dwordx4 v[124:127], v[8:9], off
	global_load_dwordx4 v[140:143], v[0:1], off offset:192
	global_load_dwordx4 v[132:135], v[0:1], off offset:224
	v_lshl_add_u64 v[0:1], s[76:77], 0, v[2:3]
	v_lshl_add_u64 v[0:1], v[0:1], 0, v[130:131]
	v_lshl_add_u64 v[2:3], s[76:77], 0, v[4:5]
	v_lshl_add_u64 v[2:3], v[2:3], 0, v[130:131]
	global_load_dwordx4 v[112:115], v[0:1], off
	global_load_dwordx4 v[116:119], v[2:3], off
	v_mov_b32_e32 v0, 0xf0
	v_sub_co_u32_e32 v0, vcc, s31, v0
	s_cmpk_gt_i32 s31, 0xbf
	v_readfirstlane_b32 s5, v0
	s_cselect_b64 s[16:17], -1, 0
	s_mul_i32 s14, s5, 6
	s_lshl_b32 s5, s5, 2
	s_add_i32 s15, s5, 0x60
	s_lshl_b32 s5, s31, 2
	s_addk_i32 s14, 0x120
	s_addk_i32 s1, 0xfa90
	s_add_i32 s36, s31, 0xffffff70
	s_add_i32 s37, s5, 0xfffffd00
	s_add_i32 s40, s31, 0x9e
	s_xor_b32 s84, s83, 0xf00
	s_add_u32 s5, s59, s52
	s_addc_u32 s41, s18, s53
	s_add_u32 s52, s5, s74
	s_addc_u32 s53, s41, s75
	s_add_u32 s5, s59, s78
	s_addc_u32 s41, s18, s79
	s_add_u32 s60, s5, s74
	s_addc_u32 s61, s41, s75
	s_lshl_b64 s[6:7], s[6:7], 24
	s_add_u32 s5, s19, s6
	s_addc_u32 s41, s28, s7
	s_lshl_b32 s6, s50, 7
	s_ashr_i32 s7, s6, 31
	s_lshl_b64 s[6:7], s[6:7], 1
	s_add_u32 s85, s5, s6
	s_addc_u32 s86, s41, s7
	s_ashr_i32 s5, s4, 31
	s_lshl_b64 s[4:5], s[4:5], 14
	s_add_u32 s78, s20, s4
	s_addc_u32 s79, s21, s5
	s_and_b64 s[4:5], vcc, exec
	s_cselect_b32 s6, 7, 6
	s_and_b64 s[4:5], s[70:71], exec
	s_cselect_b32 s7, s40, s37
	s_and_b64 s[4:5], vcc, exec
	s_cselect_b32 s15, s36, s15
	s_and_b64 s[4:5], s[70:71], exec
	s_cselect_b32 s36, 0, s37
	s_and_b64 s[4:5], vcc, exec
	v_and_b32_e32 v1, 0x70, v10
	s_movk_i32 s4, 0xf0
	s_waitcnt vmcnt(0)
	s_cselect_b32 s1, s1, s14
	s_cmpk_lt_i32 s31, 0xd0
	v_lshlrev_b32_e32 v0, 8, v11
	v_bitop3_b32 v1, v12, v1, s4 bitop3:0x6c
	s_mov_b32 s0, 0
	s_cselect_b32 s87, 3, s25
	s_cselect_b32 s64, s24, s29
	v_add3_u32 v0, 0, v0, v1
	s_cselect_b32 s65, s3, s6
	s_cselect_b32 s14, s7, s15
	s_cselect_b32 s15, s36, s1
	s_xor_b64 s[88:89], s[16:17], -1
	s_mov_b64 s[40:41], 0xb000
	s_waitcnt vmcnt(0) lgkmcnt(0)
	ds_write_b128 v0, v[120:123] offset:32768
	ds_write_b128 v0, v[124:127] offset:40960
	s_waitcnt lgkmcnt(0)
	s_barrier
	s_branch .LBB0_854

.LBB0_919:
	s_waitcnt vmcnt(0)
	v_add_u32_e32 v112, s74, v205
	v_add_u32_e32 v80, 1, v112
	v_ashrrev_i32_e32 v81, 31, v80
	v_add_u32_e32 v84, 33, v112
	v_lshlrev_b64 v[80:81], 8, v[80:81]
	v_ashrrev_i32_e32 v85, 31, v84
	v_lshl_add_u64 v[82:83], v[186:187], 0, v[80:81]
	v_lshlrev_b64 v[84:85], 8, v[84:85]
	v_lshl_add_u64 v[80:81], v[188:189], 0, v[80:81]
	v_lshl_add_u64 v[86:87], v[186:187], 0, v[84:85]
	global_load_dwordx4 v[164:167], v[82:83], off
	global_load_dwordx4 v[168:171], v[86:87], off
	v_lshl_add_u64 v[82:83], v[188:189], 0, v[84:85]
	global_load_dwordx4 v[172:175], v[80:81], off
	global_load_dwordx4 v[176:179], v[82:83], off
	ds_read2_b64 v[94:97], v185 offset1:32
	v_mov_b64_e32 v[82:83], s[10:11]
	v_mov_b64_e32 v[100:101], s[10:11]
	v_mov_b64_e32 v[80:81], s[8:9]
	v_mov_b64_e32 v[98:99], s[8:9]
	s_waitcnt lgkmcnt(0)
	v_or_b32_e32 v81, 1.0, v95
	v_mov_b32_e32 v80, v94
	v_or_b32_e32 v99, 1.0, v97
	v_mov_b32_e32 v98, v96
	v_cndmask_b32_e64 v129, 0, v218, s[6:7]
	v_cndmask_b32_e64 v130, 0, v219, s[6:7]
	s_nop 1
	v_mfma_f32_32x32x16_bf16 v[80:95], v[80:83], v[128:131], 0
	v_mfma_f32_32x32x16_bf16 v[96:111], v[98:101], v[128:131], 0
	s_setprio 1
	ds_read_b128 v[114:117], v212 offset:49152
	ds_read_b128 v[118:121], v212 offset:57344
	ds_read_b128 v[122:125], v211 offset:49152
	s_waitcnt lgkmcnt(2)
	v_mfma_f32_32x32x16_bf16 v[80:95], v[114:117], v[160:163], v[80:95]
	ds_read_b128 v[114:117], v211 offset:57344
	s_waitcnt lgkmcnt(2)
	v_mfma_f32_32x32x16_bf16 v[96:111], v[118:121], v[160:163], v[96:111]
	ds_read_b128 v[118:121], v210 offset:49152
	s_waitcnt lgkmcnt(2)
	v_mfma_f32_32x32x16_bf16 v[80:95], v[122:125], v[156:159], v[80:95]
	ds_read_b128 v[122:125], v210 offset:57344
	s_waitcnt lgkmcnt(2)
	v_mfma_f32_32x32x16_bf16 v[96:111], v[114:117], v[156:159], v[96:111]
	ds_read_b128 v[114:117], v209 offset:49152
	s_waitcnt lgkmcnt(2)
	v_mfma_f32_32x32x16_bf16 v[80:95], v[118:121], v[152:155], v[80:95]
	ds_read_b128 v[118:121], v209 offset:57344
	s_waitcnt lgkmcnt(2)
	v_mfma_f32_32x32x16_bf16 v[96:111], v[122:125], v[152:155], v[96:111]
	ds_read_b128 v[122:125], v212 offset:49280
	s_waitcnt lgkmcnt(2)
	v_mfma_f32_32x32x16_bf16 v[80:95], v[114:117], v[148:151], v[80:95]
	ds_read_b128 v[114:117], v212 offset:57472
	s_waitcnt lgkmcnt(2)
	v_mfma_f32_32x32x16_bf16 v[96:111], v[118:121], v[148:151], v[96:111]
	ds_read_b128 v[118:121], v211 offset:49280
	s_waitcnt lgkmcnt(2)
	v_mfma_f32_32x32x16_bf16 v[80:95], v[122:125], v[144:147], v[80:95]
	ds_read_b128 v[122:125], v211 offset:57472
	s_waitcnt lgkmcnt(2)
	v_mfma_f32_32x32x16_bf16 v[96:111], v[114:117], v[144:147], v[96:111]
	ds_read_b128 v[114:117], v210 offset:49280
	s_waitcnt lgkmcnt(2)
	v_mfma_f32_32x32x16_bf16 v[80:95], v[118:121], v[136:139], v[80:95]
	ds_read_b128 v[118:121], v210 offset:57472
	s_waitcnt lgkmcnt(2)
	v_mfma_f32_32x32x16_bf16 v[96:111], v[122:125], v[136:139], v[96:111]
	ds_read_b128 v[122:125], v209 offset:49280
	s_waitcnt lgkmcnt(2)
	v_mfma_f32_32x32x16_bf16 v[80:95], v[114:117], v[140:143], v[80:95]
	ds_read_b128 v[114:117], v209 offset:57472
	s_waitcnt lgkmcnt(2)
	v_mfma_f32_32x32x16_bf16 v[96:111], v[118:121], v[140:143], v[96:111]
	s_waitcnt lgkmcnt(1)
	v_mfma_f32_32x32x16_bf16 v[80:95], v[122:125], v[132:135], v[80:95]
	s_waitcnt lgkmcnt(0)
	v_mfma_f32_32x32x16_bf16 v[96:111], v[114:117], v[132:135], v[96:111]
	s_setprio 0
	v_exp_f32_e32 v113, v64
	v_add_f32_e32 v64, 0, v237
	v_add_f32_e32 v64, v239, v64
	v_add_f32_e32 v64, v235, v64
	v_add_f32_e32 v64, v238, v64
	v_add_f32_e32 v64, v233, v64
	v_add_f32_e32 v64, v236, v64
	v_add_f32_e32 v64, v232, v64
	v_add_f32_e32 v64, v234, v64
	v_add_f32_e32 v64, v229, v64
	v_add_f32_e32 v64, v231, v64
	v_add_f32_e32 v64, v227, v64
	v_add_f32_e32 v64, v230, v64
	v_add_f32_e32 v64, v225, v64
	v_exp_f32_e32 v114, v65
	v_add_f32_e32 v64, v228, v64
	v_exp_f32_e32 v115, v66
	v_add_f32_e32 v64, v224, v64
	v_exp_f32_e32 v116, v67
	v_add_f32_e32 v64, v226, v64
	v_exp_f32_e32 v117, v68
	v_add_f32_e32 v64, v113, v64
	v_exp_f32_e32 v118, v69
	v_add_f32_e32 v64, v114, v64
	v_exp_f32_e32 v119, v70
	v_add_f32_e32 v64, v115, v64
	v_exp_f32_e32 v120, v71
	v_add_f32_e32 v64, v116, v64
	v_exp_f32_e32 v121, v72
	v_add_f32_e32 v64, v117, v64
	v_exp_f32_e32 v122, v73
	v_add_f32_e32 v64, v118, v64
	v_exp_f32_e32 v123, v74
	v_add_f32_e32 v64, v119, v64
	v_exp_f32_e32 v124, v75
	v_add_f32_e32 v64, v120, v64
	v_exp_f32_e32 v125, v76
	v_add_f32_e32 v64, v121, v64
	v_exp_f32_e32 v126, v77
	v_add_f32_e32 v64, v122, v64
	v_exp_f32_e32 v127, v78
	v_add_f32_e32 v64, v123, v64
	v_exp_f32_e32 v79, v79
	v_add_f32_e32 v64, v124, v64
	v_add_f32_e32 v64, v125, v64
	v_add_f32_e32 v64, v126, v64
	v_add_f32_e32 v64, v127, v64
	v_add_f32_e32 v221, v79, v64
	v_mov_b32_e32 v222, v221
	s_nop 1
	v_permlane32_swap_b32_e32 v221, v222
	v_cvt_pk_bf16_f32 v64, v237, v239
	v_cvt_pk_bf16_f32 v65, v235, v238
	v_cvt_pk_bf16_f32 v66, v233, v236
	v_cvt_pk_bf16_f32 v67, v232, v234
	v_cvt_pk_bf16_f32 v68, v229, v231
	v_cvt_pk_bf16_f32 v69, v227, v230
	v_cvt_pk_bf16_f32 v70, v225, v228
	v_cvt_pk_bf16_f32 v71, v224, v226
	v_cvt_pk_bf16_f32 v72, v113, v114
	v_cvt_pk_bf16_f32 v73, v115, v116
	v_cvt_pk_bf16_f32 v74, v117, v118
	v_cvt_pk_bf16_f32 v75, v119, v120
	v_cvt_pk_bf16_f32 v76, v121, v122
	v_cvt_pk_bf16_f32 v77, v123, v124
	v_cvt_pk_bf16_f32 v78, v125, v126
	v_cvt_pk_bf16_f32 v79, v127, v79
	s_nop 0
	v_permlane32_swap_b32_e32 v64, v66
	v_permlane32_swap_b32_e32 v65, v67
	v_permlane32_swap_b32_e32 v68, v70
	v_permlane32_swap_b32_e32 v69, v71
	v_permlane32_swap_b32_e32 v72, v74
	v_permlane32_swap_b32_e32 v73, v75
	v_permlane32_swap_b32_e32 v76, v78
	v_permlane32_swap_b32_e32 v77, v79
	s_setprio 1
	ds_read_b64_tr_b16 v[114:115], v203 offset:0
	ds_read_b64_tr_b16 v[116:117], v203 offset:0x800
	ds_read_b64_tr_b16 v[118:119], v203 offset:0x1000
	ds_read_b64_tr_b16 v[120:121], v203 offset:0x1800
	ds_read_b64_tr_b16 v[122:123], v203 offset:0x2000
	ds_read_b64_tr_b16 v[124:125], v203 offset:0x2800
	ds_read_b64_tr_b16 v[224:225], v203 offset:0x3000
	ds_read_b64_tr_b16 v[226:227], v203 offset:0x3800
	s_waitcnt lgkmcnt(0)
	s_nop 0
	v_mfma_f32_32x32x16_bf16 v[48:63], v[64:67], v[114:117], v[48:63]
	ds_read_b64_tr_b16 v[114:115], v203 offset:0x200
	ds_read_b64_tr_b16 v[116:117], v203 offset:0xa00
	v_mfma_f32_32x32x16_bf16 v[48:63], v[68:71], v[118:121], v[48:63]
	ds_read_b64_tr_b16 v[118:119], v203 offset:0x1200
	ds_read_b64_tr_b16 v[120:121], v203 offset:0x1a00
	v_mfma_f32_32x32x16_bf16 v[48:63], v[72:75], v[122:125], v[48:63]
	ds_read_b64_tr_b16 v[122:123], v203 offset:0x2200
	ds_read_b64_tr_b16 v[124:125], v203 offset:0x2a00
	v_mfma_f32_32x32x16_bf16 v[48:63], v[76:79], v[224:227], v[48:63]
	ds_read_b64_tr_b16 v[224:225], v203 offset:0x3200
	ds_read_b64_tr_b16 v[226:227], v203 offset:0x3a00
	s_waitcnt lgkmcnt(0)
	v_mfma_f32_32x32x16_bf16 v[32:47], v[64:67], v[114:117], v[32:47]
	ds_read_b64_tr_b16 v[114:115], v203 offset:0x400
	ds_read_b64_tr_b16 v[116:117], v203 offset:0xc00
	v_mfma_f32_32x32x16_bf16 v[32:47], v[68:71], v[118:121], v[32:47]
	ds_read_b64_tr_b16 v[118:119], v203 offset:0x1400
	ds_read_b64_tr_b16 v[120:121], v203 offset:0x1c00
	v_mfma_f32_32x32x16_bf16 v[32:47], v[72:75], v[122:125], v[32:47]
	ds_read_b64_tr_b16 v[122:123], v203 offset:0x2400
	ds_read_b64_tr_b16 v[124:125], v203 offset:0x2c00
	v_mfma_f32_32x32x16_bf16 v[32:47], v[76:79], v[224:227], v[32:47]
	ds_read_b64_tr_b16 v[224:225], v203 offset:0x3400
	ds_read_b64_tr_b16 v[226:227], v203 offset:0x3c00
	s_waitcnt lgkmcnt(0)
	v_mfma_f32_32x32x16_bf16 v[16:31], v[64:67], v[114:117], v[16:31]
	ds_read_b64_tr_b16 v[114:115], v203 offset:0x600
	ds_read_b64_tr_b16 v[116:117], v203 offset:0xe00
	v_mfma_f32_32x32x16_bf16 v[16:31], v[68:71], v[118:121], v[16:31]
	ds_read_b64_tr_b16 v[118:119], v203 offset:0x1600
	ds_read_b64_tr_b16 v[120:121], v203 offset:0x1e00
	v_mfma_f32_32x32x16_bf16 v[16:31], v[72:75], v[122:125], v[16:31]
	ds_read_b64_tr_b16 v[122:123], v203 offset:0x2600
	ds_read_b64_tr_b16 v[124:125], v203 offset:0x2e00
	v_mfma_f32_32x32x16_bf16 v[16:31], v[76:79], v[224:227], v[16:31]
	ds_read_b64_tr_b16 v[224:225], v203 offset:0x3600
	ds_read_b64_tr_b16 v[226:227], v203 offset:0x3e00
	s_waitcnt lgkmcnt(0)
	v_mfma_f32_32x32x16_bf16 v[0:15], v[64:67], v[114:117], v[0:15]
	v_mfma_f32_32x32x16_bf16 v[0:15], v[68:71], v[118:121], v[0:15]
	v_mfma_f32_32x32x16_bf16 v[0:15], v[72:75], v[122:125], v[0:15]
	v_mfma_f32_32x32x16_bf16 v[0:15], v[76:79], v[224:227], v[0:15]
	s_setprio 0
	s_sub_i32 s3, s74, 63
	s_cmp_le_i32 s74, s42
	s_cselect_b64 s[4:5], -1, 0
	s_cmp_gt_i32 s3, s16
	s_cselect_b64 s[36:37], -1, 0
	s_and_b64 s[4:5], s[4:5], s[36:37]
	s_and_b64 vcc, exec, s[4:5]
	s_cbranch_vccnz .LBB0_921
	v_add_u32_e32 v64, 0x7b, v220
	v_cmp_gt_u32_e32 vcc, s29, v64
	v_add_u32_e32 v64, 0x5b, v220
	s_nop 0
	v_cndmask_b32_e32 v80, v196, v80, vcc
	v_cmp_gt_u32_e32 vcc, s29, v64
	v_add_u32_e32 v64, 0x7a, v220
	s_nop 0
	v_cndmask_b32_e32 v96, v196, v96, vcc
	v_cmp_gt_u32_e32 vcc, s29, v64
	v_add_u32_e32 v64, 0x5a, v220
	s_nop 0
	v_cndmask_b32_e32 v81, v196, v81, vcc
	v_cmp_gt_u32_e32 vcc, s29, v64
	v_add_u32_e32 v64, 0x79, v220
	s_nop 0
	v_cndmask_b32_e32 v97, v196, v97, vcc
	v_cmp_gt_u32_e32 vcc, s29, v64
	v_add_u32_e32 v64, 0x59, v220
	s_nop 0
	v_cndmask_b32_e32 v82, v196, v82, vcc
	v_cmp_gt_u32_e32 vcc, s29, v64
	v_add_u32_e32 v64, 0x78, v220
	s_nop 0
	v_cndmask_b32_e32 v98, v196, v98, vcc
	v_cmp_gt_u32_e32 vcc, s29, v64
	v_add_u32_e32 v64, 0x58, v220
	s_nop 0
	v_cndmask_b32_e32 v83, v196, v83, vcc
	v_cmp_gt_u32_e32 vcc, s29, v64
	v_add_u32_e32 v64, 0x73, v220
	s_nop 0
	v_cndmask_b32_e32 v99, v196, v99, vcc
	v_cmp_gt_u32_e32 vcc, s29, v64
	v_add_u32_e32 v64, 0x53, v220
	s_nop 0
	v_cndmask_b32_e32 v84, v196, v84, vcc
	v_cmp_gt_u32_e32 vcc, s29, v64
	v_add_u32_e32 v64, 0x72, v220
	s_nop 0
	v_cndmask_b32_e32 v100, v196, v100, vcc
	v_cmp_gt_u32_e32 vcc, s29, v64
	v_add_u32_e32 v64, 0x52, v220
	s_nop 0
	v_cndmask_b32_e32 v85, v196, v85, vcc
	v_cmp_gt_u32_e32 vcc, s29, v64
	v_add_u32_e32 v64, 0x71, v220
	s_nop 0
	v_cndmask_b32_e32 v101, v196, v101, vcc
	v_cmp_gt_u32_e32 vcc, s29, v64
	v_add_u32_e32 v64, 0x51, v220
	s_nop 0
	v_cndmask_b32_e32 v86, v196, v86, vcc
	v_cmp_gt_u32_e32 vcc, s29, v64
	v_add_u32_e32 v64, 0x70, v220
	s_nop 0
	v_cndmask_b32_e32 v102, v196, v102, vcc
	v_cmp_gt_u32_e32 vcc, s29, v64
	v_add_u32_e32 v64, 0x50, v220
	s_nop 0
	v_cndmask_b32_e32 v87, v196, v87, vcc
	v_cmp_gt_u32_e32 vcc, s29, v64
	v_add_u32_e32 v64, 0x6b, v220
	s_nop 0
	v_cndmask_b32_e32 v103, v196, v103, vcc
	v_cmp_gt_u32_e32 vcc, s29, v64
	v_add_u32_e32 v64, 0x4b, v220
	s_nop 0
	v_cndmask_b32_e32 v88, v196, v88, vcc
	v_cmp_gt_u32_e32 vcc, s29, v64
	v_add_u32_e32 v64, 0x6a, v220
	s_nop 0
	v_cndmask_b32_e32 v104, v196, v104, vcc
	v_cmp_gt_u32_e32 vcc, s29, v64
	v_add_u32_e32 v64, 0x4a, v220
	s_nop 0
	v_cndmask_b32_e32 v89, v196, v89, vcc
	v_cmp_gt_u32_e32 vcc, s29, v64
	v_add_u32_e32 v64, 0x69, v220
	s_nop 0
	v_cndmask_b32_e32 v105, v196, v105, vcc
	v_cmp_gt_u32_e32 vcc, s29, v64
	v_add_u32_e32 v64, 0x49, v220
	s_nop 0
	v_cndmask_b32_e32 v90, v196, v90, vcc
	v_cmp_gt_u32_e32 vcc, s29, v64
	v_add_u32_e32 v64, 0x68, v220
	s_nop 0
	v_cndmask_b32_e32 v106, v196, v106, vcc
	v_cmp_gt_u32_e32 vcc, s29, v64
	v_add_u32_e32 v64, 0x48, v220
	s_nop 0
	v_cndmask_b32_e32 v91, v196, v91, vcc
	v_cmp_gt_u32_e32 vcc, s29, v64
	v_add_u32_e32 v64, 0x63, v220
	s_nop 0
	v_cndmask_b32_e32 v107, v196, v107, vcc
	v_cmp_gt_u32_e32 vcc, s29, v64
	v_add_u32_e32 v64, 0x43, v220
	s_nop 0
	v_cndmask_b32_e32 v92, v196, v92, vcc
	v_cmp_gt_u32_e32 vcc, s29, v64
	v_add_u32_e32 v64, 0x62, v220
	s_nop 0
	v_cndmask_b32_e32 v108, v196, v108, vcc
	v_cmp_gt_u32_e32 vcc, s29, v64
	v_add_u32_e32 v64, 0x42, v220
	s_nop 0
	v_cndmask_b32_e32 v93, v196, v93, vcc
	v_cmp_gt_u32_e32 vcc, s29, v64
	v_add_u32_e32 v64, 0x61, v220
	s_nop 0
	v_cndmask_b32_e32 v109, v196, v109, vcc
	v_cmp_gt_u32_e32 vcc, s29, v64
	v_add_u32_e32 v64, 0x41, v220
	s_nop 0
	v_cndmask_b32_e32 v94, v196, v94, vcc
	v_cmp_gt_u32_e32 vcc, s29, v64
	v_add_u32_e32 v64, 0x60, v220
	s_nop 0
	v_cndmask_b32_e32 v110, v196, v110, vcc
	v_cmp_gt_u32_e32 vcc, s29, v64
	v_add_u32_e32 v64, 64, v220
	s_nop 0
	v_cndmask_b32_e32 v95, v196, v95, vcc
	v_cmp_gt_u32_e32 vcc, s29, v64
	s_nop 1
	v_cndmask_b32_e32 v111, v196, v111, vcc

.LBB0_928:
	ds_read2_b64 v[64:67], v185 offset0:64 offset1:96
	v_mov_b64_e32 v[70:71], s[10:11]
	v_mov_b64_e32 v[74:75], s[10:11]
	v_mov_b64_e32 v[68:69], s[8:9]
	v_mov_b64_e32 v[72:73], s[8:9]
	s_waitcnt lgkmcnt(0)
	v_or_b32_e32 v69, 1.0, v65
	v_mov_b32_e32 v68, v64
	v_or_b32_e32 v73, 1.0, v67
	v_mov_b32_e32 v72, v66
	v_cndmask_b32_e64 v129, 0, v218, s[6:7]
	v_cndmask_b32_e64 v130, 0, v219, s[6:7]
	s_add_i32 s3, s74, 1
	s_nop 0
	v_mfma_f32_32x32x16_bf16 v[112:127], v[68:71], v[128:131], 0
	v_mfma_f32_32x32x16_bf16 v[64:79], v[72:75], v[128:131], 0
	s_setprio 1
	ds_read_b128 v[224:227], v212 offset:32768
	ds_read_b128 v[228:231], v212 offset:40960
	ds_read_b128 v[232:235], v211 offset:32768
	ds_read_b128 v[236:239], v211 offset:40960
	s_waitcnt lgkmcnt(3)
	v_mfma_f32_32x32x16_bf16 v[112:127], v[224:227], v[160:163], v[112:127]
	ds_read_b128 v[224:227], v210 offset:32768
	s_waitcnt lgkmcnt(3)
	v_mfma_f32_32x32x16_bf16 v[64:79], v[228:231], v[160:163], v[64:79]
	ds_read_b128 v[228:231], v210 offset:40960
	s_waitcnt lgkmcnt(3)
	v_mfma_f32_32x32x16_bf16 v[112:127], v[232:235], v[156:159], v[112:127]
	ds_read_b128 v[232:235], v209 offset:32768
	s_waitcnt lgkmcnt(3)
	v_mfma_f32_32x32x16_bf16 v[64:79], v[236:239], v[156:159], v[64:79]
	ds_read_b128 v[236:239], v209 offset:40960
	s_waitcnt lgkmcnt(3)
	v_mfma_f32_32x32x16_bf16 v[112:127], v[224:227], v[152:155], v[112:127]
	ds_read_b128 v[224:227], v212 offset:32896
	s_waitcnt lgkmcnt(3)
	v_mfma_f32_32x32x16_bf16 v[64:79], v[228:231], v[152:155], v[64:79]
	ds_read_b128 v[228:231], v212 offset:41088
	s_waitcnt lgkmcnt(3)
	v_mfma_f32_32x32x16_bf16 v[112:127], v[232:235], v[148:151], v[112:127]
	ds_read_b128 v[232:235], v211 offset:32896
	s_waitcnt lgkmcnt(3)
	v_mfma_f32_32x32x16_bf16 v[64:79], v[236:239], v[148:151], v[64:79]
	ds_read_b128 v[236:239], v211 offset:41088
	s_waitcnt lgkmcnt(3)
	v_mfma_f32_32x32x16_bf16 v[112:127], v[224:227], v[144:147], v[112:127]
	ds_read_b128 v[224:227], v210 offset:32896
	s_waitcnt lgkmcnt(3)
	v_mfma_f32_32x32x16_bf16 v[64:79], v[228:231], v[144:147], v[64:79]
	ds_read_b128 v[228:231], v210 offset:41088
	s_waitcnt lgkmcnt(3)
	v_mfma_f32_32x32x16_bf16 v[112:127], v[232:235], v[136:139], v[112:127]
	ds_read_b128 v[232:235], v209 offset:32896
	s_waitcnt lgkmcnt(3)
	v_mfma_f32_32x32x16_bf16 v[64:79], v[236:239], v[136:139], v[64:79]
	ds_read_b128 v[236:239], v209 offset:41088
	s_waitcnt lgkmcnt(3)
	v_mfma_f32_32x32x16_bf16 v[112:127], v[224:227], v[140:143], v[112:127]
	s_waitcnt lgkmcnt(2)
	v_mfma_f32_32x32x16_bf16 v[64:79], v[228:231], v[140:143], v[64:79]
	s_waitcnt lgkmcnt(1)
	v_mfma_f32_32x32x16_bf16 v[112:127], v[232:235], v[132:135], v[112:127]
	s_waitcnt lgkmcnt(0)
	v_mfma_f32_32x32x16_bf16 v[64:79], v[236:239], v[132:135], v[64:79]
	s_setprio 0
	v_add_f32_e32 v129, 0, v80
	v_add_f32_e32 v129, v81, v129
	v_add_f32_e32 v129, v82, v129
	v_add_f32_e32 v129, v83, v129
	v_add_f32_e32 v129, v84, v129
	v_add_f32_e32 v129, v85, v129
	v_add_f32_e32 v129, v86, v129
	v_add_f32_e32 v129, v87, v129
	v_add_f32_e32 v129, v88, v129
	v_add_f32_e32 v129, v89, v129
	v_add_f32_e32 v129, v90, v129
	v_add_f32_e32 v129, v91, v129
	v_exp_f32_e32 v96, v96
	v_add_f32_e32 v129, v92, v129
	v_exp_f32_e32 v97, v97
	v_add_f32_e32 v129, v93, v129
	v_exp_f32_e32 v98, v98
	v_add_f32_e32 v129, v94, v129
	v_exp_f32_e32 v99, v99
	v_add_f32_e32 v129, v95, v129
	v_exp_f32_e32 v100, v100
	v_add_f32_e32 v129, v96, v129
	v_exp_f32_e32 v101, v101
	v_add_f32_e32 v129, v97, v129
	v_exp_f32_e32 v102, v102
	v_add_f32_e32 v129, v98, v129
	v_exp_f32_e32 v103, v103
	v_add_f32_e32 v129, v99, v129
	v_exp_f32_e32 v104, v104
	v_add_f32_e32 v129, v100, v129
	v_exp_f32_e32 v105, v105
	v_add_f32_e32 v129, v101, v129
	v_exp_f32_e32 v106, v106
	v_add_f32_e32 v129, v102, v129
	v_exp_f32_e32 v107, v107
	v_add_f32_e32 v129, v103, v129
	v_exp_f32_e32 v108, v108
	v_add_f32_e32 v129, v104, v129
	v_exp_f32_e32 v109, v109
	v_add_f32_e32 v129, v105, v129
	v_exp_f32_e32 v110, v110
	v_add_f32_e32 v129, v106, v129
	v_exp_f32_e32 v111, v111
	v_add_f32_e32 v129, v107, v129
	v_add_f32_e32 v129, v108, v129
	v_add_f32_e32 v129, v109, v129
	v_add_f32_e32 v129, v110, v129
	v_add_f32_e32 v129, v111, v129
	v_mov_b32_e32 v130, v129
	s_nop 1
	v_permlane32_swap_b32_e32 v129, v130
	v_cvt_pk_bf16_f32 v224, v80, v81
	v_cvt_pk_bf16_f32 v225, v82, v83
	v_cvt_pk_bf16_f32 v226, v84, v85
	v_cvt_pk_bf16_f32 v227, v86, v87
	v_cvt_pk_bf16_f32 v228, v88, v89
	v_cvt_pk_bf16_f32 v229, v90, v91
	v_cvt_pk_bf16_f32 v230, v92, v93
	v_cvt_pk_bf16_f32 v231, v94, v95
	v_cvt_pk_bf16_f32 v232, v96, v97
	v_cvt_pk_bf16_f32 v233, v98, v99
	v_cvt_pk_bf16_f32 v234, v100, v101
	v_cvt_pk_bf16_f32 v235, v102, v103
	v_cvt_pk_bf16_f32 v236, v104, v105
	v_cvt_pk_bf16_f32 v237, v106, v107
	v_cvt_pk_bf16_f32 v238, v108, v109
	v_cvt_pk_bf16_f32 v239, v110, v111
	s_nop 0
	v_permlane32_swap_b32_e32 v224, v226
	v_permlane32_swap_b32_e32 v225, v227
	v_permlane32_swap_b32_e32 v228, v230
	v_permlane32_swap_b32_e32 v229, v231
	v_permlane32_swap_b32_e32 v232, v234
	v_permlane32_swap_b32_e32 v233, v235
	v_permlane32_swap_b32_e32 v236, v238
	v_permlane32_swap_b32_e32 v237, v239
	s_setprio 1
	ds_read_b64_tr_b16 v[240:241], v203 offset:0x4000
	ds_read_b64_tr_b16 v[242:243], v203 offset:0x4800
	ds_read_b64_tr_b16 v[244:245], v203 offset:0x5000
	ds_read_b64_tr_b16 v[246:247], v203 offset:0x5800
	ds_read_b64_tr_b16 v[248:249], v203 offset:0x6000
	ds_read_b64_tr_b16 v[250:251], v203 offset:0x6800
	ds_read_b64_tr_b16 v[192:193], v203 offset:0x7000
	ds_read_b64_tr_b16 v[194:195], v203 offset:0x7800
	s_waitcnt lgkmcnt(0)
	s_nop 0
	v_mfma_f32_32x32x16_bf16 v[48:63], v[224:227], v[240:243], v[48:63]
	v_mfma_f32_32x32x16_bf16 v[48:63], v[228:231], v[244:247], v[48:63]
	v_mfma_f32_32x32x16_bf16 v[48:63], v[232:235], v[248:251], v[48:63]
	v_mfma_f32_32x32x16_bf16 v[48:63], v[236:239], v[192:195], v[48:63]
	ds_read_b64_tr_b16 v[192:193], v203 offset:0x4200
	ds_read_b64_tr_b16 v[194:195], v203 offset:0x4a00
	ds_read_b64_tr_b16 v[240:241], v203 offset:0x5200
	ds_read_b64_tr_b16 v[242:243], v203 offset:0x5a00
	ds_read_b64_tr_b16 v[244:245], v203 offset:0x6200
	ds_read_b64_tr_b16 v[246:247], v203 offset:0x6a00
	ds_read_b64_tr_b16 v[248:249], v203 offset:0x7200
	ds_read_b64_tr_b16 v[250:251], v203 offset:0x7a00
	s_waitcnt lgkmcnt(0)
	s_nop 0
	v_mfma_f32_32x32x16_bf16 v[32:47], v[224:227], v[192:195], v[32:47]
	ds_read_b64_tr_b16 v[192:193], v203 offset:0x4400
	ds_read_b64_tr_b16 v[194:195], v203 offset:0x4c00
	v_mfma_f32_32x32x16_bf16 v[32:47], v[228:231], v[240:243], v[32:47]
	ds_read_b64_tr_b16 v[240:241], v203 offset:0x5400
	ds_read_b64_tr_b16 v[242:243], v203 offset:0x5c00
	v_mfma_f32_32x32x16_bf16 v[32:47], v[232:235], v[244:247], v[32:47]
	ds_read_b64_tr_b16 v[244:245], v203 offset:0x6400
	ds_read_b64_tr_b16 v[246:247], v203 offset:0x6c00
	v_mfma_f32_32x32x16_bf16 v[32:47], v[236:239], v[248:251], v[32:47]
	ds_read_b64_tr_b16 v[248:249], v203 offset:0x7400
	ds_read_b64_tr_b16 v[250:251], v203 offset:0x7c00
	s_waitcnt lgkmcnt(0)
	v_mfma_f32_32x32x16_bf16 v[16:31], v[224:227], v[192:195], v[16:31]
	ds_read_b64_tr_b16 v[192:193], v203 offset:0x4600
	ds_read_b64_tr_b16 v[194:195], v203 offset:0x4e00
	v_mfma_f32_32x32x16_bf16 v[16:31], v[228:231], v[240:243], v[16:31]
	ds_read_b64_tr_b16 v[240:241], v203 offset:0x5600
	ds_read_b64_tr_b16 v[242:243], v203 offset:0x5e00
	v_mfma_f32_32x32x16_bf16 v[16:31], v[232:235], v[244:247], v[16:31]
	ds_read_b64_tr_b16 v[244:245], v203 offset:0x6600
	ds_read_b64_tr_b16 v[246:247], v203 offset:0x6e00
	v_mfma_f32_32x32x16_bf16 v[16:31], v[236:239], v[248:251], v[16:31]
	ds_read_b64_tr_b16 v[248:249], v203 offset:0x7600
	ds_read_b64_tr_b16 v[250:251], v203 offset:0x7e00
	s_waitcnt lgkmcnt(0)
	v_mfma_f32_32x32x16_bf16 v[0:15], v[224:227], v[192:195], v[0:15]
	v_mfma_f32_32x32x16_bf16 v[0:15], v[228:231], v[240:243], v[0:15]
	v_mfma_f32_32x32x16_bf16 v[0:15], v[232:235], v[244:247], v[0:15]
	v_mfma_f32_32x32x16_bf16 v[0:15], v[236:239], v[248:251], v[0:15]
	s_setprio 0
	s_add_i32 s4, s74, 64
	s_cmp_le_i32 s4, s42
	s_cselect_b64 s[4:5], -1, 0
	s_cmp_gt_i32 s3, s16
	s_cselect_b64 s[36:37], -1, 0
	s_and_b64 s[4:5], s[4:5], s[36:37]
	s_and_b64 vcc, exec, s[4:5]
	s_cbranch_vccnz .LBB0_930
	v_add_u32_e32 v192, 59, v220
	v_cmp_gt_u32_e32 vcc, s29, v192
	v_add_u32_e32 v192, 27, v220
	s_nop 0
	v_cndmask_b32_e32 v112, v196, v112, vcc
	v_cmp_gt_u32_e32 vcc, s29, v192
	v_add_u32_e32 v192, 58, v220
	s_nop 0
	v_cndmask_b32_e32 v64, v196, v64, vcc
	v_cmp_gt_u32_e32 vcc, s29, v192
	v_add_u32_e32 v192, 26, v220
	s_nop 0
	v_cndmask_b32_e32 v113, v196, v113, vcc
	v_cmp_gt_u32_e32 vcc, s29, v192
	v_add_u32_e32 v192, 57, v220
	s_nop 0
	v_cndmask_b32_e32 v65, v196, v65, vcc
	v_cmp_gt_u32_e32 vcc, s29, v192
	v_add_u32_e32 v192, 25, v220
	s_nop 0
	v_cndmask_b32_e32 v114, v196, v114, vcc
	v_cmp_gt_u32_e32 vcc, s29, v192
	v_add_u32_e32 v192, 56, v220
	s_nop 0
	v_cndmask_b32_e32 v66, v196, v66, vcc
	v_cmp_gt_u32_e32 vcc, s29, v192
	v_add_u32_e32 v192, 24, v220
	s_nop 0
	v_cndmask_b32_e32 v115, v196, v115, vcc
	v_cmp_gt_u32_e32 vcc, s29, v192
	v_add_u32_e32 v192, 51, v220
	s_nop 0
	v_cndmask_b32_e32 v67, v196, v67, vcc
	v_cmp_gt_u32_e32 vcc, s29, v192
	v_add_u32_e32 v192, 19, v220
	s_nop 0
	v_cndmask_b32_e32 v116, v196, v116, vcc
	v_cmp_gt_u32_e32 vcc, s29, v192
	v_add_u32_e32 v192, 50, v220
	s_nop 0
	v_cndmask_b32_e32 v68, v196, v68, vcc
	v_cmp_gt_u32_e32 vcc, s29, v192
	v_add_u32_e32 v192, 18, v220
	s_nop 0
	v_cndmask_b32_e32 v117, v196, v117, vcc
	v_cmp_gt_u32_e32 vcc, s29, v192
	v_add_u32_e32 v192, 49, v220
	s_nop 0
	v_cndmask_b32_e32 v69, v196, v69, vcc
	v_cmp_gt_u32_e32 vcc, s29, v192
	v_add_u32_e32 v192, 17, v220
	s_nop 0
	v_cndmask_b32_e32 v118, v196, v118, vcc
	v_cmp_gt_u32_e32 vcc, s29, v192
	v_add_u32_e32 v192, 48, v220
	s_nop 0
	v_cndmask_b32_e32 v70, v196, v70, vcc
	v_cmp_gt_u32_e32 vcc, s29, v192
	v_add_u32_e32 v192, 16, v220
	s_nop 0
	v_cndmask_b32_e32 v119, v196, v119, vcc
	v_cmp_gt_u32_e32 vcc, s29, v192
	v_add_u32_e32 v192, 43, v220
	s_nop 0
	v_cndmask_b32_e32 v71, v196, v71, vcc
	v_cmp_gt_u32_e32 vcc, s29, v192
	v_add_u32_e32 v192, 11, v220
	s_nop 0
	v_cndmask_b32_e32 v120, v196, v120, vcc
	v_cmp_gt_u32_e32 vcc, s29, v192
	v_add_u32_e32 v192, 42, v220
	s_nop 0
	v_cndmask_b32_e32 v72, v196, v72, vcc
	v_cmp_gt_u32_e32 vcc, s29, v192
	v_add_u32_e32 v192, 10, v220
	s_nop 0
	v_cndmask_b32_e32 v121, v196, v121, vcc
	v_cmp_gt_u32_e32 vcc, s29, v192
	v_add_u32_e32 v192, 41, v220
	s_nop 0
	v_cndmask_b32_e32 v73, v196, v73, vcc
	v_cmp_gt_u32_e32 vcc, s29, v192
	v_add_u32_e32 v192, 9, v220
	s_nop 0
	v_cndmask_b32_e32 v122, v196, v122, vcc
	v_cmp_gt_u32_e32 vcc, s29, v192
	v_add_u32_e32 v192, 40, v220
	s_nop 0
	v_cndmask_b32_e32 v74, v196, v74, vcc
	v_cmp_gt_u32_e32 vcc, s29, v192
	v_add_u32_e32 v192, 8, v220
	s_nop 0
	v_cndmask_b32_e32 v123, v196, v123, vcc
	v_cmp_gt_u32_e32 vcc, s29, v192
	v_add_u32_e32 v192, 35, v220
	s_nop 0
	v_cndmask_b32_e32 v75, v196, v75, vcc
	v_cmp_gt_u32_e32 vcc, s29, v192
	v_add_u32_e32 v192, 3, v220
	s_nop 0
	v_cndmask_b32_e32 v124, v196, v124, vcc
	v_cmp_gt_u32_e32 vcc, s29, v192
	v_add_u32_e32 v192, 34, v220
	s_nop 0
	v_cndmask_b32_e32 v76, v196, v76, vcc
	v_cmp_gt_u32_e32 vcc, s29, v192
	v_add_u32_e32 v192, 2, v220
	s_nop 0
	v_cndmask_b32_e32 v125, v196, v125, vcc
	v_cmp_gt_u32_e32 vcc, s29, v192
	v_add_u32_e32 v192, 33, v220
	s_nop 0
	v_cndmask_b32_e32 v77, v196, v77, vcc
	v_cmp_gt_u32_e32 vcc, s29, v192
	v_add_u32_e32 v192, 1, v220
	s_nop 0
	v_cndmask_b32_e32 v126, v196, v126, vcc
	v_cmp_gt_u32_e32 vcc, s29, v192
	v_add_u32_e32 v192, 32, v220
	s_nop 0
	v_cndmask_b32_e32 v78, v196, v78, vcc
	v_cmp_gt_u32_e32 vcc, s29, v192
	s_nop 1
	v_cndmask_b32_e32 v127, v196, v127, vcc
	v_cmp_gt_u32_e32 vcc, s29, v220
	s_nop 1
	v_cndmask_b32_e32 v79, v196, v79, vcc

.LBB0_939:
	s_bitcmp0_b32 s43, 0
	s_cselect_b64 s[4:5], -1, 0
	s_and_b64 vcc, exec, s[4:5]
	s_cbranch_vccz .LBB0_941
	v_lshl_add_u32 v86, s43, 9, v213
	v_add_u32_e32 v80, 0xfffffe00, v86
	ds_read_b64 v[84:85], v80
	v_mov_b64_e32 v[82:83], s[10:11]
	v_mov_b64_e32 v[80:81], s[8:9]
	v_add_u32_e32 v80, 0xffffff00, v86
	ds_read_b64 v[100:101], v80
	v_mov_b64_e32 v[98:99], s[10:11]
	v_mov_b64_e32 v[96:97], s[8:9]
	s_waitcnt lgkmcnt(0)
	v_or_b32_e32 v81, 1.0, v85
	v_mov_b32_e32 v80, v84
	v_or_b32_e32 v97, 1.0, v101
	v_mov_b32_e32 v96, v100
	v_cndmask_b32_e64 v129, 0, v218, s[6:7]
	v_cndmask_b32_e64 v130, 0, v219, s[6:7]
	s_nop 1
	v_mfma_f32_32x32x16_bf16 v[80:95], v[80:83], v[128:131], 0
	v_mfma_f32_32x32x16_bf16 v[96:111], v[96:99], v[128:131], 0
	s_setprio 1
	s_waitcnt vmcnt(0)
	ds_read_b128 v[112:115], v212 offset:49152
	ds_read_b128 v[116:119], v212 offset:57344
	ds_read_b128 v[120:123], v211 offset:49152
	ds_read_b128 v[124:127], v211 offset:57344
	s_waitcnt lgkmcnt(3)
	v_mfma_f32_32x32x16_bf16 v[80:95], v[112:115], v[160:163], v[80:95]
	ds_read_b128 v[112:115], v210 offset:49152
	s_waitcnt lgkmcnt(3)
	v_mfma_f32_32x32x16_bf16 v[96:111], v[116:119], v[160:163], v[96:111]
	ds_read_b128 v[116:119], v210 offset:57344
	s_waitcnt lgkmcnt(3)
	v_mfma_f32_32x32x16_bf16 v[80:95], v[120:123], v[156:159], v[80:95]
	ds_read_b128 v[120:123], v209 offset:49152
	s_waitcnt lgkmcnt(3)
	v_mfma_f32_32x32x16_bf16 v[96:111], v[124:127], v[156:159], v[96:111]
	ds_read_b128 v[124:127], v209 offset:57344
	s_waitcnt lgkmcnt(3)
	v_mfma_f32_32x32x16_bf16 v[80:95], v[112:115], v[152:155], v[80:95]
	ds_read_b128 v[112:115], v212 offset:49280
	s_waitcnt lgkmcnt(3)
	v_mfma_f32_32x32x16_bf16 v[96:111], v[116:119], v[152:155], v[96:111]
	ds_read_b128 v[116:119], v212 offset:57472
	s_waitcnt lgkmcnt(3)
	v_mfma_f32_32x32x16_bf16 v[80:95], v[120:123], v[148:151], v[80:95]
	ds_read_b128 v[120:123], v211 offset:49280
	s_waitcnt lgkmcnt(3)
	v_mfma_f32_32x32x16_bf16 v[96:111], v[124:127], v[148:151], v[96:111]
	ds_read_b128 v[124:127], v211 offset:57472
	s_waitcnt lgkmcnt(3)
	v_mfma_f32_32x32x16_bf16 v[80:95], v[112:115], v[144:147], v[80:95]
	ds_read_b128 v[112:115], v210 offset:49280
	s_waitcnt lgkmcnt(3)
	v_mfma_f32_32x32x16_bf16 v[96:111], v[116:119], v[144:147], v[96:111]
	ds_read_b128 v[116:119], v210 offset:57472
	s_waitcnt lgkmcnt(3)
	v_mfma_f32_32x32x16_bf16 v[80:95], v[120:123], v[136:139], v[80:95]
	ds_read_b128 v[120:123], v209 offset:49280
	s_waitcnt lgkmcnt(3)
	v_mfma_f32_32x32x16_bf16 v[96:111], v[124:127], v[136:139], v[96:111]
	ds_read_b128 v[124:127], v209 offset:57472
	s_waitcnt lgkmcnt(3)
	v_mfma_f32_32x32x16_bf16 v[80:95], v[112:115], v[140:143], v[80:95]
	s_waitcnt lgkmcnt(2)
	v_mfma_f32_32x32x16_bf16 v[96:111], v[116:119], v[140:143], v[96:111]
	s_waitcnt lgkmcnt(1)
	v_mfma_f32_32x32x16_bf16 v[80:95], v[120:123], v[132:135], v[80:95]
	s_waitcnt lgkmcnt(0)
	v_mfma_f32_32x32x16_bf16 v[96:111], v[124:127], v[132:135], v[96:111]
	s_setprio 0

.LBB0_1086:
	s_cmpk_lt_i32 s31, 0xb0
	s_cbranch_scc0 .LBB0_838
	v_readlane_b32 s0, v254, 8
	v_readlane_b32 s1, v254, 9
	s_and_b64 vcc, exec, s[0:1]
	s_cbranch_vccnz .LBB0_1102
	v_mbcnt_lo_u32_b32 v0, -1, 0
	v_mbcnt_hi_u32_b32 v0, -1, v0
	s_nop 0
	v_cmp_eq_u32_e32 vcc, 0, v0
	s_and_saveexec_b64 s[4:5], vcc
	s_cbranch_execz .LBB0_1101
	v_mov_b64_e32 v[0:1], s[12:13]
	global_load_dword v0, v[0:1], off sc1
	s_waitcnt vmcnt(0) lgkmcnt(0)
	v_cmp_gt_u32_e32 vcc, 16, v0
	s_and_saveexec_b64 s[6:7], vcc
	s_cbranch_execz .LBB0_1100
	s_mov_b32 s0, 1
	s_mov_b64 s[46:47], 0
	s_branch .LBB0_1092

.LBB0_1102:
	s_add_i32 s0, s31, 0xa0
	s_and_b32 s0, s0, 0xff
	s_lshl_b32 s1, s31, 2
	s_addk_i32 s1, 0xfde3
	s_cmpk_lt_i32 s31, 0xa0
	s_cselect_b32 s0, s0, s1
	s_lshl_b32 s70, s0, 8
	s_and_b32 s70, s70, 0xf00
	s_ashr_i32 s4, s0, 6
	s_bfe_u32 s1, s0, 0x20004
	s_ashr_i32 s5, s4, 31
	s_lshl_b32 s0, s1, 14
	s_lshl_b64 s[50:51], s[4:5], 12
	s_or_b32 s0, s0, 0x70000
	s_add_u32 s0, s50, s0
	v_readlane_b32 s3, v255, 28
	s_addc_u32 s7, s51, 0
	s_lshl_b32 s3, s4, 8
	s_or_b32 s6, s0, s70
	s_lshl_b32 s0, s1, 10
	s_ashr_i32 s14, s3, 31
	s_add_u32 s4, s0, s3
	s_addc_u32 s5, 0, s14
	s_lshl_b64 s[4:5], s[4:5], 8
	s_add_u32 s72, s82, s4
	s_addc_u32 s73, s26, s5
	s_bitset1_b32 s0, 12
	s_add_u32 s4, s0, s3
	s_addc_u32 s5, 0, s14
	s_lshl_b64 s[4:5], s[4:5], 8
	s_add_u32 s46, s82, s4
	s_addc_u32 s47, s26, s5
	s_lshl_b64 s[4:5], s[6:7], 8
	s_barrier
	s_add_u32 s4, s59, s4
	v_mbcnt_lo_u32_b32 v4, -1, 0
	v_mbcnt_hi_u32_b32 v4, -1, v4
	s_addc_u32 s5, s18, s5
	v_and_or_b32 v130, v4, 31, s58
	v_ashrrev_i32_e32 v2, 2, v4
	v_lshlrev_b64 v[0:1], 8, v[130:131]
	v_and_b32_e32 v2, -8, v2
	v_ashrrev_i32_e32 v3, 31, v2
	v_lshl_add_u64 v[0:1], s[4:5], 0, v[0:1]
	v_lshl_add_u64 v[0:1], v[2:3], 1, v[0:1]
	v_readlane_b32 s0, v254, 7
	global_load_dwordx4 v[144:147], v[0:1], off
	global_load_dwordx4 v[140:143], v[0:1], off offset:32
	global_load_dwordx4 v[136:139], v[0:1], off offset:64
	global_load_dwordx4 v[132:135], v[0:1], off offset:96
	global_load_dwordx4 v[124:127], v[0:1], off offset:128
	global_load_dwordx4 v[120:123], v[0:1], off offset:160
	global_load_dwordx4 v[116:119], v[0:1], off offset:192
	global_load_dwordx4 v[112:115], v[0:1], off offset:224
	v_add_u32_e32 v1, s0, v4
	v_ashrrev_i32_e32 v0, 4, v1
	v_lshlrev_b32_e32 v2, 4, v4
	v_and_b32_e32 v1, 0x70, v1
	s_movk_i32 s3, 0xf0
	v_bitop3_b32 v17, v2, v1, s3 bitop3:0x6c
	v_ashrrev_i32_e32 v1, 31, v0
	v_lshlrev_b64 v[8:9], 8, v[0:1]
	s_mov_b64 s[4:5], 0x2000
	v_lshlrev_b32_e32 v16, 8, v0
	v_and_b32_e32 v130, 0xf0, v2
	v_lshl_add_u64 v[0:1], s[46:47], 0, v[8:9]
	v_lshl_add_u64 v[12:13], v[8:9], 0, s[4:5]
	v_lshl_add_u64 v[8:9], s[72:73], 0, v[8:9]
	v_lshl_add_u64 v[4:5], s[46:47], 0, v[12:13]
	v_lshl_add_u64 v[8:9], v[8:9], 0, v[130:131]
	v_lshl_add_u64 v[12:13], s[72:73], 0, v[12:13]
	global_load_dwordx4 v[8:11], v[8:9], off
	v_lshl_add_u64 v[12:13], v[12:13], 0, v[130:131]
	v_lshl_add_u64 v[0:1], v[0:1], 0, v[130:131]
	v_lshl_add_u64 v[4:5], v[4:5], 0, v[130:131]
	global_load_dwordx4 v[12:15], v[12:13], off
	v_add3_u32 v16, 0, v16, v17
	global_load_dwordx4 v[0:3], v[0:1], off
	s_nop 0
	global_load_dwordx4 v[4:7], v[4:5], off
	s_waitcnt vmcnt(0)
	s_waitcnt vmcnt(0) lgkmcnt(0)
	ds_write_b128 v16, v[8:11] offset:32768
	ds_write_b128 v16, v[12:15] offset:40960
	s_waitcnt lgkmcnt(0)
	s_barrier
	v_mbcnt_lo_u32_b32 v165, -1, 0
	v_mbcnt_hi_u32_b32 v165, -1, v165
	s_nop 0
	v_add_u32_e32 v49, s0, v165
	s_movk_i32 s0, 0xff
	v_cmp_lt_i32_e32 vcc, s0, v49
	v_lshlrev_b32_e32 v48, 3, v165
	s_and_saveexec_b64 s[4:5], vcc
	s_xor_b64 s[4:5], exec, s[4:5]
	v_lshlrev_b32_e32 v48, 3, v165
	s_andn2_saveexec_b64 s[4:5], s[4:5]
	s_cbranch_execz .LBB0_1108
	v_readlane_b32 s0, v255, 27
	s_mov_b64 s[6:7], 0
	s_nop 0
	v_add_u32_e32 v8, s0, v165
	v_readlane_b32 s0, v254, 24
	s_nop 1
	v_add_u32_e32 v9, s0, v48

.LBB0_1112:
	v_lshlrev_b32_e32 v52, 8, v166
	v_and_b32_e32 v49, 0x70, v49
	v_bitop3_b32 v49, v130, v52, v49 bitop3:0xde
	v_and_b32_e32 v51, 0xc0, v51
	v_lshlrev_b32_e32 v52, 1, v165
	v_and_or_b32 v51, v48, 24, v51
	v_and_b32_e32 v52, 32, v52
	v_and_b32_e32 v48, 0x100, v48
	s_cmp_lg_u32 0, -1
	v_or3_b32 v48, v51, v52, v48
	s_cselect_b32 s0, 0, 0
	v_add_u32_e32 v175, s0, v48
	v_exp_f32_e32 v48, v16
	v_exp_f32_e32 v51, v17
	v_exp_f32_e32 v52, v18
	v_exp_f32_e32 v53, v19
	v_exp_f32_e32 v54, v20
	v_exp_f32_e32 v55, v21
	v_exp_f32_e32 v56, v22
	v_exp_f32_e32 v57, v23
	v_exp_f32_e32 v58, v24
	v_exp_f32_e32 v59, v25
	v_exp_f32_e32 v60, v26
	v_exp_f32_e32 v61, v27
	v_exp_f32_e32 v62, v28
	v_exp_f32_e32 v63, v29
	s_waitcnt vmcnt(0)
	v_add_u32_e32 v174, 0, v49
	v_lshl_add_u64 v[148:149], s[46:47], 0, v[130:131]
	v_lshl_add_u64 v[156:157], s[72:73], 0, v[130:131]
	v_exp_f32_e32 v153, v30
	v_exp_f32_e32 v154, v31
	s_waitcnt vmcnt(0)
	ds_write_b128 v185, v[32:35] offset:16384
	ds_write_b128 v186, v[36:39] offset:16384
	ds_write_b128 v174, v[40:43] offset:49152
	ds_write_b128 v174, v[44:47] offset:57344
	s_waitcnt lgkmcnt(0)
	s_barrier
	v_lshlrev_b64 v[16:17], 8, v[166:167]
	v_lshl_add_u64 v[18:19], v[16:17], 0, s[34:35]
	v_lshl_add_u64 v[20:21], v[148:149], 0, v[18:19]
	v_lshl_add_u64 v[16:17], v[16:17], 0, s[54:55]
	v_lshl_add_u64 v[18:19], v[156:157], 0, v[18:19]
	v_lshl_add_u64 v[22:23], v[148:149], 0, v[16:17]
	global_load_dwordx4 v[96:99], v[20:21], off
	global_load_dwordx4 v[100:103], v[22:23], off
	v_lshl_add_u64 v[16:17], v[156:157], 0, v[16:17]
	global_load_dwordx4 v[104:107], v[18:19], off
	global_load_dwordx4 v[108:111], v[16:17], off
	s_add_i32 s0, 0, 0x10800
	v_add_u32_e32 v198, s0, v50
	ds_read2_b64 v[16:19], v198 offset0:64 offset1:96
	v_mov_b64_e32 v[22:23], s[10:11]
	v_mov_b64_e32 v[26:27], s[10:11]
	v_mov_b64_e32 v[20:21], s[8:9]
	v_mov_b64_e32 v[24:25], s[8:9]
	s_waitcnt lgkmcnt(0)
	v_or_b32_e32 v21, 1.0, v17
	v_mov_b32_e32 v20, v16
	v_or_b32_e32 v25, 1.0, v19
	v_mov_b32_e32 v24, v18
	v_mov_b64_e32 v[28:29], v[128:129]
	v_cndmask_b32_e64 v16, 0, v197, s[6:7]
	v_mov_b64_e32 v[30:31], v[130:131]
	v_mov_b32_e32 v30, v16
	s_nop 1
	v_mfma_f32_32x32x16_bf16 v[64:79], v[20:23], v[28:31], 0
	v_mfma_f32_32x32x16_bf16 v[80:95], v[24:27], v[28:31], 0
	s_setprio 1
	ds_read_b128 v[16:19], v181 offset:49152
	ds_read_b128 v[20:23], v181 offset:57344
	ds_read_b128 v[24:27], v180 offset:49152
	ds_read_b128 v[28:31], v180 offset:57344
	s_waitcnt lgkmcnt(3)
	v_mfma_f32_32x32x16_bf16 v[64:79], v[16:19], v[144:147], v[64:79]
	ds_read_b128 v[16:19], v179 offset:49152
	s_waitcnt lgkmcnt(3)
	v_mfma_f32_32x32x16_bf16 v[80:95], v[20:23], v[144:147], v[80:95]
	ds_read_b128 v[20:23], v179 offset:57344
	s_waitcnt lgkmcnt(3)
	v_mfma_f32_32x32x16_bf16 v[64:79], v[24:27], v[140:143], v[64:79]
	ds_read_b128 v[24:27], v169 offset:49152
	s_waitcnt lgkmcnt(3)
	v_mfma_f32_32x32x16_bf16 v[80:95], v[28:31], v[140:143], v[80:95]
	ds_read_b128 v[28:31], v169 offset:57344
	s_waitcnt lgkmcnt(3)
	v_mfma_f32_32x32x16_bf16 v[64:79], v[16:19], v[136:139], v[64:79]
	ds_read_b128 v[16:19], v181 offset:49280
	s_waitcnt lgkmcnt(3)
	v_mfma_f32_32x32x16_bf16 v[80:95], v[20:23], v[136:139], v[80:95]
	ds_read_b128 v[20:23], v181 offset:57472
	s_waitcnt lgkmcnt(3)
	v_mfma_f32_32x32x16_bf16 v[64:79], v[24:27], v[132:135], v[64:79]
	ds_read_b128 v[24:27], v180 offset:49280
	s_waitcnt lgkmcnt(3)
	v_mfma_f32_32x32x16_bf16 v[80:95], v[28:31], v[132:135], v[80:95]
	ds_read_b128 v[28:31], v180 offset:57472
	s_waitcnt lgkmcnt(3)
	v_mfma_f32_32x32x16_bf16 v[64:79], v[16:19], v[124:127], v[64:79]
	ds_read_b128 v[16:19], v179 offset:49280
	s_waitcnt lgkmcnt(3)
	v_mfma_f32_32x32x16_bf16 v[80:95], v[20:23], v[124:127], v[80:95]
	ds_read_b128 v[20:23], v179 offset:57472
	s_waitcnt lgkmcnt(3)
	v_mfma_f32_32x32x16_bf16 v[64:79], v[24:27], v[120:123], v[64:79]
	ds_read_b128 v[24:27], v169 offset:49280
	s_waitcnt lgkmcnt(3)
	v_mfma_f32_32x32x16_bf16 v[80:95], v[28:31], v[120:123], v[80:95]
	ds_read_b128 v[28:31], v169 offset:57472
	s_waitcnt lgkmcnt(3)
	v_mfma_f32_32x32x16_bf16 v[64:79], v[16:19], v[116:119], v[64:79]
	s_waitcnt lgkmcnt(2)
	v_mfma_f32_32x32x16_bf16 v[80:95], v[20:23], v[116:119], v[80:95]
	s_waitcnt lgkmcnt(1)
	v_mfma_f32_32x32x16_bf16 v[64:79], v[24:27], v[112:115], v[64:79]
	s_waitcnt lgkmcnt(0)
	v_mfma_f32_32x32x16_bf16 v[80:95], v[28:31], v[112:115], v[80:95]
	s_setprio 0
	v_add_f32_e32 v16, 0, v48
	v_add_f32_e32 v16, v51, v16
	v_add_f32_e32 v16, v52, v16
	v_add_f32_e32 v16, v53, v16
	v_add_f32_e32 v16, v54, v16
	v_add_f32_e32 v16, v55, v16
	v_add_f32_e32 v16, v56, v16
	v_add_f32_e32 v16, v57, v16
	v_add_f32_e32 v16, v58, v16
	v_add_f32_e32 v16, v59, v16
	v_add_f32_e32 v16, v60, v16
	v_add_f32_e32 v16, v61, v16
	v_exp_f32_e32 v0, v0
	v_add_f32_e32 v16, v62, v16
	v_exp_f32_e32 v1, v1
	v_add_f32_e32 v16, v63, v16
	v_exp_f32_e32 v2, v2
	v_add_f32_e32 v16, v153, v16
	v_exp_f32_e32 v3, v3
	v_add_f32_e32 v16, v154, v16
	v_exp_f32_e32 v4, v4
	v_add_f32_e32 v16, v0, v16
	v_exp_f32_e32 v5, v5
	v_add_f32_e32 v16, v1, v16
	v_exp_f32_e32 v6, v6
	v_add_f32_e32 v16, v2, v16
	v_exp_f32_e32 v7, v7
	v_add_f32_e32 v16, v3, v16
	v_exp_f32_e32 v8, v8
	v_add_f32_e32 v16, v4, v16
	v_exp_f32_e32 v9, v9
	v_add_f32_e32 v16, v5, v16
	v_exp_f32_e32 v10, v10
	v_add_f32_e32 v16, v6, v16
	v_exp_f32_e32 v11, v11
	v_add_f32_e32 v16, v7, v16
	v_exp_f32_e32 v12, v12
	v_add_f32_e32 v16, v8, v16
	v_exp_f32_e32 v13, v13
	v_add_f32_e32 v16, v9, v16
	v_exp_f32_e32 v14, v14
	v_add_f32_e32 v16, v10, v16
	v_exp_f32_e32 v15, v15
	v_add_f32_e32 v16, v11, v16
	v_add_f32_e32 v16, v12, v16
	v_add_f32_e32 v16, v13, v16
	v_add_f32_e32 v16, v14, v16
	v_add_f32_e32 v176, v15, v16
	v_mov_b32_e32 v177, v176
	v_cvt_pk_bf16_f32 v48, v48, v51
	v_cvt_pk_bf16_f32 v49, v52, v53
	v_cvt_pk_bf16_f32 v50, v54, v55
	v_cvt_pk_bf16_f32 v51, v56, v57
	s_nop 1
	v_permlane32_swap_b32_e32 v176, v177
	v_permlane32_swap_b32_e32 v48, v50
	v_permlane32_swap_b32_e32 v49, v51
	v_cvt_pk_bf16_f32 v150, v58, v59
	v_cvt_pk_bf16_f32 v151, v60, v61
	v_cvt_pk_bf16_f32 v152, v62, v63
	v_cvt_pk_bf16_f32 v153, v153, v154
	v_cvt_pk_bf16_f32 v158, v0, v1
	v_cvt_pk_bf16_f32 v159, v2, v3
	v_cvt_pk_bf16_f32 v160, v4, v5
	v_cvt_pk_bf16_f32 v161, v6, v7
	v_cvt_pk_bf16_f32 v192, v8, v9
	v_cvt_pk_bf16_f32 v193, v10, v11
	v_cvt_pk_bf16_f32 v194, v12, v13
	v_cvt_pk_bf16_f32 v195, v14, v15
	s_nop 0
	v_permlane32_swap_b32_e32 v150, v152
	v_permlane32_swap_b32_e32 v151, v153
	v_permlane32_swap_b32_e32 v158, v160
	v_permlane32_swap_b32_e32 v159, v161
	v_permlane32_swap_b32_e32 v192, v194
	v_permlane32_swap_b32_e32 v193, v195
	s_setprio 1
	ds_read_b64_tr_b16 v[0:1], v175 offset:0
	ds_read_b64_tr_b16 v[2:3], v175 offset:0x800
	ds_read_b64_tr_b16 v[16:17], v175 offset:0x1000
	ds_read_b64_tr_b16 v[18:19], v175 offset:0x1800
	ds_read_b64_tr_b16 v[20:21], v175 offset:0x2000
	ds_read_b64_tr_b16 v[22:23], v175 offset:0x2800
	ds_read_b64_tr_b16 v[24:25], v175 offset:0x3000
	ds_read_b64_tr_b16 v[26:27], v175 offset:0x3800
	s_waitcnt lgkmcnt(0)
	s_nop 0
	v_mfma_f32_32x32x16_bf16 v[0:15], v[48:51], v[0:3], 0
	v_mfma_f32_32x32x16_bf16 v[0:15], v[150:153], v[16:19], v[0:15]
	ds_read_b64_tr_b16 v[16:17], v175 offset:0x200
	ds_read_b64_tr_b16 v[18:19], v175 offset:0xa00
	ds_read_b64_tr_b16 v[32:33], v175 offset:0x1200
	ds_read_b64_tr_b16 v[34:35], v175 offset:0x1a00
	ds_read_b64_tr_b16 v[36:37], v175 offset:0x2200
	ds_read_b64_tr_b16 v[38:39], v175 offset:0x2a00
	ds_read_b64_tr_b16 v[40:41], v175 offset:0x3200
	v_mfma_f32_32x32x16_bf16 v[0:15], v[158:161], v[20:23], v[0:15]
	ds_read_b64_tr_b16 v[42:43], v175 offset:0x3a00
	s_waitcnt lgkmcnt(0)
	v_mfma_f32_32x32x16_bf16 v[0:15], v[192:195], v[24:27], v[0:15]
	v_mfma_f32_32x32x16_bf16 v[16:31], v[48:51], v[16:19], 0
	v_mfma_f32_32x32x16_bf16 v[16:31], v[150:153], v[32:35], v[16:31]
	ds_read_b64_tr_b16 v[32:33], v175 offset:0x400
	ds_read_b64_tr_b16 v[34:35], v175 offset:0xc00
	ds_read_b64_tr_b16 v[52:53], v175 offset:0x1400
	ds_read_b64_tr_b16 v[54:55], v175 offset:0x1c00
	ds_read_b64_tr_b16 v[56:57], v175 offset:0x2400
	ds_read_b64_tr_b16 v[58:59], v175 offset:0x2c00
	ds_read_b64_tr_b16 v[60:61], v175 offset:0x3400
	v_mfma_f32_32x32x16_bf16 v[16:31], v[158:161], v[36:39], v[16:31]
	ds_read_b64_tr_b16 v[62:63], v175 offset:0x3c00
	s_waitcnt lgkmcnt(0)
	v_mfma_f32_32x32x16_bf16 v[16:31], v[192:195], v[40:43], v[16:31]
	v_mfma_f32_32x32x16_bf16 v[32:47], v[48:51], v[32:35], 0
	v_mfma_f32_32x32x16_bf16 v[32:47], v[150:153], v[52:55], v[32:47]
	ds_read_b64_tr_b16 v[52:53], v175 offset:0x600
	ds_read_b64_tr_b16 v[54:55], v175 offset:0xe00
	ds_read_b64_tr_b16 v[200:201], v175 offset:0x1600
	ds_read_b64_tr_b16 v[202:203], v175 offset:0x1e00
	ds_read_b64_tr_b16 v[206:207], v175 offset:0x2600
	ds_read_b64_tr_b16 v[208:209], v175 offset:0x2e00
	ds_read_b64_tr_b16 v[210:211], v175 offset:0x3600
	v_mfma_f32_32x32x16_bf16 v[32:47], v[158:161], v[56:59], v[32:47]
	ds_read_b64_tr_b16 v[212:213], v175 offset:0x3e00
	s_waitcnt lgkmcnt(0)
	v_mfma_f32_32x32x16_bf16 v[32:47], v[192:195], v[60:63], v[32:47]
	v_mfma_f32_32x32x16_bf16 v[48:63], v[48:51], v[52:55], 0
	v_mfma_f32_32x32x16_bf16 v[48:63], v[150:153], v[200:203], v[48:63]
	v_mfma_f32_32x32x16_bf16 v[48:63], v[158:161], v[206:209], v[48:63]
	v_mfma_f32_32x32x16_bf16 v[48:63], v[192:195], v[210:213], v[48:63]
	s_setprio 0
	v_readlane_b32 s4, v255, 23
	v_readlane_b32 s5, v255, 24
	s_andn2_b64 vcc, exec, s[4:5]
	s_cbranch_vccnz .LBB0_1114
	v_subrev_u32_e32 v129, 64, v173
	s_mov_b32 s0, 0x100000
	v_cmp_gt_u32_e32 vcc, s0, v129
	v_add_u32_e32 v129, 0xffffffa0, v173
	s_nop 0
	v_cndmask_b32_e32 v64, v196, v64, vcc
	v_cmp_gt_u32_e32 vcc, s0, v129
	v_add_u32_e32 v129, 0xffffffbf, v173
	s_nop 0
	v_cndmask_b32_e32 v80, v196, v80, vcc
	v_cmp_gt_u32_e32 vcc, s0, v129
	v_add_u32_e32 v129, 0xffffff9f, v173
	s_nop 0
	v_cndmask_b32_e32 v65, v196, v65, vcc
	v_cmp_gt_u32_e32 vcc, s0, v129
	v_add_u32_e32 v129, 0xffffffbe, v173
	s_nop 0
	v_cndmask_b32_e32 v81, v196, v81, vcc
	v_cmp_gt_u32_e32 vcc, s0, v129
	v_add_u32_e32 v129, 0xffffff9e, v173
	s_nop 0
	v_cndmask_b32_e32 v66, v196, v66, vcc
	v_cmp_gt_u32_e32 vcc, s0, v129
	v_add_u32_e32 v129, 0xffffffbd, v173
	s_nop 0
	v_cndmask_b32_e32 v82, v196, v82, vcc
	v_cmp_gt_u32_e32 vcc, s0, v129
	v_add_u32_e32 v129, 0xffffff9d, v173
	s_nop 0
	v_cndmask_b32_e32 v67, v196, v67, vcc
	v_cmp_gt_u32_e32 vcc, s0, v129
	v_add_u32_e32 v129, 0xffffffb8, v173
	s_nop 0
	v_cndmask_b32_e32 v83, v196, v83, vcc
	v_cmp_gt_u32_e32 vcc, s0, v129
	v_add_u32_e32 v129, 0xffffff98, v173
	s_nop 0
	v_cndmask_b32_e32 v68, v196, v68, vcc
	v_cmp_gt_u32_e32 vcc, s0, v129
	v_add_u32_e32 v129, 0xffffffb7, v173
	s_nop 0
	v_cndmask_b32_e32 v84, v196, v84, vcc
	v_cmp_gt_u32_e32 vcc, s0, v129
	v_add_u32_e32 v129, 0xffffff97, v173
	s_nop 0
	v_cndmask_b32_e32 v69, v196, v69, vcc
	v_cmp_gt_u32_e32 vcc, s0, v129
	v_add_u32_e32 v129, 0xffffffb6, v173
	s_nop 0
	v_cndmask_b32_e32 v85, v196, v85, vcc
	v_cmp_gt_u32_e32 vcc, s0, v129
	v_add_u32_e32 v129, 0xffffff96, v173
	s_nop 0
	v_cndmask_b32_e32 v70, v196, v70, vcc
	v_cmp_gt_u32_e32 vcc, s0, v129
	v_add_u32_e32 v129, 0xffffffb5, v173
	s_nop 0
	v_cndmask_b32_e32 v86, v196, v86, vcc
	v_cmp_gt_u32_e32 vcc, s0, v129
	v_add_u32_e32 v129, 0xffffff95, v173
	s_nop 0
	v_cndmask_b32_e32 v71, v196, v71, vcc
	v_cmp_gt_u32_e32 vcc, s0, v129
	v_add_u32_e32 v129, 0xffffffb0, v173
	s_nop 0
	v_cndmask_b32_e32 v87, v196, v87, vcc
	v_cmp_gt_u32_e32 vcc, s0, v129
	v_add_u32_e32 v129, 0xffffff90, v173
	s_nop 0
	v_cndmask_b32_e32 v72, v196, v72, vcc
	v_cmp_gt_u32_e32 vcc, s0, v129
	v_add_u32_e32 v129, 0xffffffaf, v173
	s_nop 0
	v_cndmask_b32_e32 v88, v196, v88, vcc
	v_cmp_gt_u32_e32 vcc, s0, v129
	v_add_u32_e32 v129, 0xffffff8f, v173
	s_nop 0
	v_cndmask_b32_e32 v73, v196, v73, vcc
	v_cmp_gt_u32_e32 vcc, s0, v129
	v_add_u32_e32 v129, 0xffffffae, v173
	s_nop 0
	v_cndmask_b32_e32 v89, v196, v89, vcc
	v_cmp_gt_u32_e32 vcc, s0, v129
	v_add_u32_e32 v129, 0xffffff8e, v173
	s_nop 0
	v_cndmask_b32_e32 v74, v196, v74, vcc
	v_cmp_gt_u32_e32 vcc, s0, v129
	v_add_u32_e32 v129, 0xffffffad, v173
	s_nop 0
	v_cndmask_b32_e32 v90, v196, v90, vcc
	v_cmp_gt_u32_e32 vcc, s0, v129
	v_add_u32_e32 v129, 0xffffff8d, v173
	s_nop 0
	v_cndmask_b32_e32 v75, v196, v75, vcc
	v_cmp_gt_u32_e32 vcc, s0, v129
	v_add_u32_e32 v129, 0xffffffa8, v173
	s_nop 0
	v_cndmask_b32_e32 v91, v196, v91, vcc
	v_cmp_gt_u32_e32 vcc, s0, v129
	v_add_u32_e32 v129, 0xffffff88, v173
	s_nop 0
	v_cndmask_b32_e32 v76, v196, v76, vcc
	v_cmp_gt_u32_e32 vcc, s0, v129
	v_add_u32_e32 v129, 0xffffffa7, v173
	s_nop 0
	v_cndmask_b32_e32 v92, v196, v92, vcc
	v_cmp_gt_u32_e32 vcc, s0, v129
	v_add_u32_e32 v129, 0xffffff87, v173
	s_nop 0
	v_cndmask_b32_e32 v77, v196, v77, vcc
	v_cmp_gt_u32_e32 vcc, s0, v129
	v_add_u32_e32 v129, 0xffffffa6, v173
	s_nop 0
	v_cndmask_b32_e32 v93, v196, v93, vcc
	v_cmp_gt_u32_e32 vcc, s0, v129
	v_add_u32_e32 v129, 0xffffff86, v173
	s_nop 0
	v_cndmask_b32_e32 v78, v196, v78, vcc
	v_cmp_gt_u32_e32 vcc, s0, v129
	v_add_u32_e32 v129, 0xffffffa5, v173
	s_nop 0
	v_cndmask_b32_e32 v94, v196, v94, vcc
	v_cmp_gt_u32_e32 vcc, s0, v129
	v_add_u32_e32 v129, 0xffffff85, v173
	s_nop 0
	v_cndmask_b32_e32 v79, v196, v79, vcc
	v_cmp_gt_u32_e32 vcc, s0, v129
	s_nop 1
	v_cndmask_b32_e32 v95, v196, v95, vcc

.LBB0_1119:
	v_exp_f32_e32 v213, v64
	v_exp_f32_e32 v215, v65
	v_exp_f32_e32 v211, v66
	v_exp_f32_e32 v214, v67
	v_exp_f32_e32 v209, v68
	v_exp_f32_e32 v212, v69
	v_exp_f32_e32 v208, v70
	v_exp_f32_e32 v210, v71
	v_exp_f32_e32 v205, v72
	v_exp_f32_e32 v207, v73
	v_exp_f32_e32 v202, v74
	v_exp_f32_e32 v206, v75
	v_exp_f32_e32 v200, v76
	v_exp_f32_e32 v203, v77
	v_exp_f32_e32 v199, v78
	v_exp_f32_e32 v201, v79
	s_waitcnt lgkmcnt(0)
	s_barrier
	v_lshlrev_b64 v[64:65], 8, v[166:167]
	s_mov_b64 s[4:5], 0xc000
	v_lshl_add_u64 v[66:67], v[64:65], 0, s[4:5]
	s_mov_b64 s[4:5], 0xe000
	v_lshl_add_u64 v[68:69], v[148:149], 0, v[66:67]
	v_lshl_add_u64 v[64:65], v[64:65], 0, s[4:5]
	v_lshl_add_u64 v[66:67], v[156:157], 0, v[66:67]
	v_lshl_add_u64 v[70:71], v[148:149], 0, v[64:65]
	global_load_dwordx4 v[148:151], v[68:69], off
	global_load_dwordx4 v[152:155], v[70:71], off
	v_lshl_add_u64 v[64:65], v[156:157], 0, v[64:65]
	global_load_dwordx4 v[156:159], v[66:67], off
	global_load_dwordx4 v[160:163], v[64:65], off
	ds_read2_b64 v[64:67], v198 offset0:128 offset1:160
	v_mov_b64_e32 v[70:71], s[10:11]
	v_mov_b64_e32 v[74:75], s[10:11]
	v_mov_b64_e32 v[68:69], s[8:9]
	v_mov_b64_e32 v[72:73], s[8:9]
	s_waitcnt lgkmcnt(0)
	v_or_b32_e32 v69, 1.0, v65
	v_mov_b32_e32 v68, v64
	v_or_b32_e32 v73, 1.0, v67
	v_mov_b32_e32 v72, v66
	v_cndmask_b32_e64 v129, 0, v189, s[6:7]
	v_mov_b64_e32 v[76:77], v[128:129]
	v_cndmask_b32_e64 v64, 0, v197, s[6:7]
	v_mov_b64_e32 v[78:79], v[130:131]
	v_mov_b32_e32 v78, v64
	s_nop 1
	v_mfma_f32_32x32x16_bf16 v[96:111], v[68:71], v[76:79], 0
	v_mfma_f32_32x32x16_bf16 v[64:79], v[72:75], v[76:79], 0
	s_setprio 1
	ds_read_b128 v[192:195], v181 offset:32768
	ds_read_b128 v[216:219], v181 offset:40960
	ds_read_b128 v[220:223], v180 offset:32768
	s_waitcnt lgkmcnt(2)
	v_mfma_f32_32x32x16_bf16 v[96:111], v[192:195], v[144:147], v[96:111]
	ds_read_b128 v[192:195], v180 offset:40960
	s_waitcnt lgkmcnt(2)
	v_mfma_f32_32x32x16_bf16 v[64:79], v[216:219], v[144:147], v[64:79]
	ds_read_b128 v[216:219], v179 offset:32768
	s_waitcnt lgkmcnt(2)
	v_mfma_f32_32x32x16_bf16 v[96:111], v[220:223], v[140:143], v[96:111]
	ds_read_b128 v[220:223], v179 offset:40960
	s_waitcnt lgkmcnt(2)
	v_mfma_f32_32x32x16_bf16 v[64:79], v[192:195], v[140:143], v[64:79]
	ds_read_b128 v[192:195], v169 offset:32768
	s_waitcnt lgkmcnt(2)
	v_mfma_f32_32x32x16_bf16 v[96:111], v[216:219], v[136:139], v[96:111]
	ds_read_b128 v[216:219], v169 offset:40960
	s_waitcnt lgkmcnt(2)
	v_mfma_f32_32x32x16_bf16 v[64:79], v[220:223], v[136:139], v[64:79]
	ds_read_b128 v[220:223], v181 offset:32896
	s_waitcnt lgkmcnt(2)
	v_mfma_f32_32x32x16_bf16 v[96:111], v[192:195], v[132:135], v[96:111]
	ds_read_b128 v[192:195], v181 offset:41088
	s_waitcnt lgkmcnt(2)
	v_mfma_f32_32x32x16_bf16 v[64:79], v[216:219], v[132:135], v[64:79]
	ds_read_b128 v[216:219], v180 offset:32896
	s_waitcnt lgkmcnt(2)
	v_mfma_f32_32x32x16_bf16 v[96:111], v[220:223], v[124:127], v[96:111]
	ds_read_b128 v[220:223], v180 offset:41088
	s_waitcnt lgkmcnt(2)
	v_mfma_f32_32x32x16_bf16 v[64:79], v[192:195], v[124:127], v[64:79]
	ds_read_b128 v[192:195], v179 offset:32896
	s_waitcnt lgkmcnt(2)
	v_mfma_f32_32x32x16_bf16 v[96:111], v[216:219], v[120:123], v[96:111]
	ds_read_b128 v[216:219], v179 offset:41088
	s_waitcnt lgkmcnt(2)
	v_mfma_f32_32x32x16_bf16 v[64:79], v[220:223], v[120:123], v[64:79]
	ds_read_b128 v[220:223], v169 offset:32896
	s_waitcnt lgkmcnt(2)
	v_mfma_f32_32x32x16_bf16 v[96:111], v[192:195], v[116:119], v[96:111]
	ds_read_b128 v[192:195], v169 offset:41088
	s_waitcnt lgkmcnt(2)
	v_mfma_f32_32x32x16_bf16 v[64:79], v[216:219], v[116:119], v[64:79]
	s_waitcnt lgkmcnt(1)
	v_mfma_f32_32x32x16_bf16 v[96:111], v[220:223], v[112:115], v[96:111]
	s_waitcnt lgkmcnt(0)
	v_mfma_f32_32x32x16_bf16 v[64:79], v[192:195], v[112:115], v[64:79]
	s_setprio 0
	v_exp_f32_e32 v129, v80
	v_add_f32_e32 v80, 0, v213
	v_add_f32_e32 v80, v215, v80
	v_add_f32_e32 v80, v211, v80
	v_add_f32_e32 v80, v214, v80
	v_add_f32_e32 v80, v209, v80
	v_add_f32_e32 v80, v212, v80
	v_add_f32_e32 v80, v208, v80
	v_add_f32_e32 v80, v210, v80
	v_add_f32_e32 v80, v205, v80
	v_add_f32_e32 v80, v207, v80
	v_add_f32_e32 v80, v202, v80
	v_add_f32_e32 v80, v206, v80
	v_add_f32_e32 v80, v200, v80
	v_exp_f32_e32 v192, v81
	v_add_f32_e32 v80, v203, v80
	v_exp_f32_e32 v193, v82
	v_add_f32_e32 v80, v199, v80
	v_exp_f32_e32 v194, v83
	v_add_f32_e32 v80, v201, v80
	v_exp_f32_e32 v195, v84
	v_add_f32_e32 v80, v129, v80
	v_exp_f32_e32 v216, v85
	v_add_f32_e32 v80, v192, v80
	v_exp_f32_e32 v217, v86
	v_add_f32_e32 v80, v193, v80
	v_exp_f32_e32 v218, v87
	v_add_f32_e32 v80, v194, v80
	v_exp_f32_e32 v219, v88
	v_add_f32_e32 v80, v195, v80
	v_exp_f32_e32 v220, v89
	v_add_f32_e32 v80, v216, v80
	v_exp_f32_e32 v221, v90
	v_add_f32_e32 v80, v217, v80
	v_exp_f32_e32 v222, v91
	v_add_f32_e32 v80, v218, v80
	v_exp_f32_e32 v223, v92
	v_add_f32_e32 v80, v219, v80
	v_exp_f32_e32 v224, v93
	v_add_f32_e32 v80, v220, v80
	v_exp_f32_e32 v225, v94
	v_add_f32_e32 v80, v221, v80
	v_exp_f32_e32 v95, v95
	v_add_f32_e32 v80, v222, v80
	v_add_f32_e32 v80, v223, v80
	v_add_f32_e32 v80, v224, v80
	v_add_f32_e32 v80, v225, v80
	v_add_f32_e32 v187, v95, v80
	v_mov_b32_e32 v188, v187
	s_nop 1
	v_permlane32_swap_b32_e32 v187, v188
	v_cvt_pk_bf16_f32 v80, v213, v215
	v_cvt_pk_bf16_f32 v81, v211, v214
	v_cvt_pk_bf16_f32 v82, v209, v212
	v_cvt_pk_bf16_f32 v83, v208, v210
	v_cvt_pk_bf16_f32 v84, v205, v207
	v_cvt_pk_bf16_f32 v85, v202, v206
	v_cvt_pk_bf16_f32 v86, v200, v203
	v_cvt_pk_bf16_f32 v87, v199, v201
	v_cvt_pk_bf16_f32 v88, v129, v192
	v_cvt_pk_bf16_f32 v89, v193, v194
	v_cvt_pk_bf16_f32 v90, v195, v216
	v_cvt_pk_bf16_f32 v91, v217, v218
	v_cvt_pk_bf16_f32 v92, v219, v220
	v_cvt_pk_bf16_f32 v93, v221, v222
	v_cvt_pk_bf16_f32 v94, v223, v224
	v_cvt_pk_bf16_f32 v95, v225, v95
	s_nop 0
	v_permlane32_swap_b32_e32 v80, v82
	v_permlane32_swap_b32_e32 v81, v83
	v_permlane32_swap_b32_e32 v84, v86
	v_permlane32_swap_b32_e32 v85, v87
	v_permlane32_swap_b32_e32 v88, v90
	v_permlane32_swap_b32_e32 v89, v91
	v_permlane32_swap_b32_e32 v92, v94
	v_permlane32_swap_b32_e32 v93, v95
	s_setprio 1
	ds_read_b64_tr_b16 v[192:193], v175 offset:0x4000
	ds_read_b64_tr_b16 v[194:195], v175 offset:0x4800
	ds_read_b64_tr_b16 v[200:201], v175 offset:0x5000
	ds_read_b64_tr_b16 v[202:203], v175 offset:0x5800
	ds_read_b64_tr_b16 v[206:207], v175 offset:0x6000
	ds_read_b64_tr_b16 v[208:209], v175 offset:0x6800
	ds_read_b64_tr_b16 v[210:211], v175 offset:0x7000
	ds_read_b64_tr_b16 v[212:213], v175 offset:0x7800
	s_waitcnt lgkmcnt(0)
	s_nop 0
	v_mfma_f32_32x32x16_bf16 v[0:15], v[80:83], v[192:195], v[0:15]
	ds_read_b64_tr_b16 v[192:193], v175 offset:0x4200
	ds_read_b64_tr_b16 v[194:195], v175 offset:0x4a00
	v_mfma_f32_32x32x16_bf16 v[0:15], v[84:87], v[200:203], v[0:15]
	ds_read_b64_tr_b16 v[200:201], v175 offset:0x5200
	ds_read_b64_tr_b16 v[202:203], v175 offset:0x5a00
	v_mfma_f32_32x32x16_bf16 v[0:15], v[88:91], v[206:209], v[0:15]
	ds_read_b64_tr_b16 v[206:207], v175 offset:0x6200
	ds_read_b64_tr_b16 v[208:209], v175 offset:0x6a00
	v_mfma_f32_32x32x16_bf16 v[0:15], v[92:95], v[210:213], v[0:15]
	ds_read_b64_tr_b16 v[210:211], v175 offset:0x7200
	ds_read_b64_tr_b16 v[212:213], v175 offset:0x7a00
	s_waitcnt lgkmcnt(0)
	v_mfma_f32_32x32x16_bf16 v[16:31], v[80:83], v[192:195], v[16:31]
	ds_read_b64_tr_b16 v[192:193], v175 offset:0x4400
	ds_read_b64_tr_b16 v[194:195], v175 offset:0x4c00
	v_mfma_f32_32x32x16_bf16 v[16:31], v[84:87], v[200:203], v[16:31]
	ds_read_b64_tr_b16 v[200:201], v175 offset:0x5400
	ds_read_b64_tr_b16 v[202:203], v175 offset:0x5c00
	v_mfma_f32_32x32x16_bf16 v[16:31], v[88:91], v[206:209], v[16:31]
	ds_read_b64_tr_b16 v[206:207], v175 offset:0x6400
	ds_read_b64_tr_b16 v[208:209], v175 offset:0x6c00
	v_mfma_f32_32x32x16_bf16 v[16:31], v[92:95], v[210:213], v[16:31]
	ds_read_b64_tr_b16 v[210:211], v175 offset:0x7400
	ds_read_b64_tr_b16 v[212:213], v175 offset:0x7c00
	s_waitcnt lgkmcnt(0)
	v_mfma_f32_32x32x16_bf16 v[32:47], v[80:83], v[192:195], v[32:47]
	ds_read_b64_tr_b16 v[192:193], v175 offset:0x4600
	ds_read_b64_tr_b16 v[194:195], v175 offset:0x4e00
	v_mfma_f32_32x32x16_bf16 v[32:47], v[84:87], v[200:203], v[32:47]
	ds_read_b64_tr_b16 v[200:201], v175 offset:0x5600
	ds_read_b64_tr_b16 v[202:203], v175 offset:0x5e00
	v_mfma_f32_32x32x16_bf16 v[32:47], v[88:91], v[206:209], v[32:47]
	ds_read_b64_tr_b16 v[206:207], v175 offset:0x6600
	ds_read_b64_tr_b16 v[208:209], v175 offset:0x6e00
	v_mfma_f32_32x32x16_bf16 v[32:47], v[92:95], v[210:213], v[32:47]
	ds_read_b64_tr_b16 v[210:211], v175 offset:0x7600
	ds_read_b64_tr_b16 v[212:213], v175 offset:0x7e00
	s_waitcnt lgkmcnt(0)
	v_mfma_f32_32x32x16_bf16 v[48:63], v[80:83], v[192:195], v[48:63]
	v_mfma_f32_32x32x16_bf16 v[48:63], v[84:87], v[200:203], v[48:63]
	v_mfma_f32_32x32x16_bf16 v[48:63], v[88:91], v[206:209], v[48:63]
	v_mfma_f32_32x32x16_bf16 v[48:63], v[92:95], v[210:213], v[48:63]
	s_setprio 0
	v_readlane_b32 s4, v255, 25
	v_readlane_b32 s5, v255, 26
	s_andn2_b64 vcc, exec, s[4:5]
	s_cbranch_vccnz .LBB0_1121
	v_add_u32_e32 v80, 0xffffff80, v173
	s_mov_b32 s0, 0x100000
	v_cmp_gt_u32_e32 vcc, s0, v80
	v_add_u32_e32 v80, 0xffffff60, v173
	s_nop 0
	v_cndmask_b32_e32 v96, v196, v96, vcc
	v_cmp_gt_u32_e32 vcc, s0, v80
	v_add_u32_e32 v80, 0xffffff7f, v173
	s_nop 0
	v_cndmask_b32_e32 v64, v196, v64, vcc
	v_cmp_gt_u32_e32 vcc, s0, v80
	v_add_u32_e32 v80, 0xffffff5f, v173
	s_nop 0
	v_cndmask_b32_e32 v97, v196, v97, vcc
	v_cmp_gt_u32_e32 vcc, s0, v80
	v_add_u32_e32 v80, 0xffffff7e, v173
	s_nop 0
	v_cndmask_b32_e32 v65, v196, v65, vcc
	v_cmp_gt_u32_e32 vcc, s0, v80
	v_add_u32_e32 v80, 0xffffff5e, v173
	s_nop 0
	v_cndmask_b32_e32 v98, v196, v98, vcc
	v_cmp_gt_u32_e32 vcc, s0, v80
	v_add_u32_e32 v80, 0xffffff7d, v173
	s_nop 0
	v_cndmask_b32_e32 v66, v196, v66, vcc
	v_cmp_gt_u32_e32 vcc, s0, v80
	v_add_u32_e32 v80, 0xffffff5d, v173
	s_nop 0
	v_cndmask_b32_e32 v99, v196, v99, vcc
	v_cmp_gt_u32_e32 vcc, s0, v80
	v_add_u32_e32 v80, 0xffffff78, v173
	s_nop 0
	v_cndmask_b32_e32 v67, v196, v67, vcc
	v_cmp_gt_u32_e32 vcc, s0, v80
	v_add_u32_e32 v80, 0xffffff58, v173
	s_nop 0
	v_cndmask_b32_e32 v100, v196, v100, vcc
	v_cmp_gt_u32_e32 vcc, s0, v80
	v_add_u32_e32 v80, 0xffffff77, v173
	s_nop 0
	v_cndmask_b32_e32 v68, v196, v68, vcc
	v_cmp_gt_u32_e32 vcc, s0, v80
	v_add_u32_e32 v80, 0xffffff57, v173
	s_nop 0
	v_cndmask_b32_e32 v101, v196, v101, vcc
	v_cmp_gt_u32_e32 vcc, s0, v80
	v_add_u32_e32 v80, 0xffffff76, v173
	s_nop 0
	v_cndmask_b32_e32 v69, v196, v69, vcc
	v_cmp_gt_u32_e32 vcc, s0, v80
	v_add_u32_e32 v80, 0xffffff56, v173
	s_nop 0
	v_cndmask_b32_e32 v102, v196, v102, vcc
	v_cmp_gt_u32_e32 vcc, s0, v80
	v_add_u32_e32 v80, 0xffffff75, v173
	s_nop 0
	v_cndmask_b32_e32 v70, v196, v70, vcc
	v_cmp_gt_u32_e32 vcc, s0, v80
	v_add_u32_e32 v80, 0xffffff55, v173
	s_nop 0
	v_cndmask_b32_e32 v103, v196, v103, vcc
	v_cmp_gt_u32_e32 vcc, s0, v80
	v_add_u32_e32 v80, 0xffffff70, v173
	s_nop 0
	v_cndmask_b32_e32 v71, v196, v71, vcc
	v_cmp_gt_u32_e32 vcc, s0, v80
	v_add_u32_e32 v80, 0xffffff50, v173
	s_nop 0
	v_cndmask_b32_e32 v104, v196, v104, vcc
	v_cmp_gt_u32_e32 vcc, s0, v80
	v_add_u32_e32 v80, 0xffffff6f, v173
	s_nop 0
	v_cndmask_b32_e32 v72, v196, v72, vcc
	v_cmp_gt_u32_e32 vcc, s0, v80
	v_add_u32_e32 v80, 0xffffff4f, v173
	s_nop 0
	v_cndmask_b32_e32 v105, v196, v105, vcc
	v_cmp_gt_u32_e32 vcc, s0, v80
	v_add_u32_e32 v80, 0xffffff6e, v173
	s_nop 0
	v_cndmask_b32_e32 v73, v196, v73, vcc
	v_cmp_gt_u32_e32 vcc, s0, v80
	v_add_u32_e32 v80, 0xffffff4e, v173
	s_nop 0
	v_cndmask_b32_e32 v106, v196, v106, vcc
	v_cmp_gt_u32_e32 vcc, s0, v80
	v_add_u32_e32 v80, 0xffffff6d, v173
	s_nop 0
	v_cndmask_b32_e32 v74, v196, v74, vcc
	v_cmp_gt_u32_e32 vcc, s0, v80
	v_add_u32_e32 v80, 0xffffff4d, v173
	s_nop 0
	v_cndmask_b32_e32 v107, v196, v107, vcc
	v_cmp_gt_u32_e32 vcc, s0, v80
	v_add_u32_e32 v80, 0xffffff68, v173
	s_nop 0
	v_cndmask_b32_e32 v75, v196, v75, vcc
	v_cmp_gt_u32_e32 vcc, s0, v80
	v_add_u32_e32 v80, 0xffffff48, v173
	s_nop 0
	v_cndmask_b32_e32 v108, v196, v108, vcc
	v_cmp_gt_u32_e32 vcc, s0, v80
	v_add_u32_e32 v80, 0xffffff67, v173
	s_nop 0
	v_cndmask_b32_e32 v76, v196, v76, vcc
	v_cmp_gt_u32_e32 vcc, s0, v80
	v_add_u32_e32 v80, 0xffffff47, v173
	s_nop 0
	v_cndmask_b32_e32 v109, v196, v109, vcc
	v_cmp_gt_u32_e32 vcc, s0, v80
	v_add_u32_e32 v80, 0xffffff66, v173
	s_nop 0
	v_cndmask_b32_e32 v77, v196, v77, vcc
	v_cmp_gt_u32_e32 vcc, s0, v80
	v_add_u32_e32 v80, 0xffffff46, v173
	s_nop 0
	v_cndmask_b32_e32 v110, v196, v110, vcc
	v_cmp_gt_u32_e32 vcc, s0, v80
	v_add_u32_e32 v80, 0xffffff65, v173
	s_nop 0
	v_cndmask_b32_e32 v78, v196, v78, vcc
	v_cmp_gt_u32_e32 vcc, s0, v80
	v_add_u32_e32 v80, 0xffffff45, v173
	s_nop 0
	v_cndmask_b32_e32 v111, v196, v111, vcc
	v_cmp_gt_u32_e32 vcc, s0, v80
	s_nop 1
	v_cndmask_b32_e32 v79, v196, v79, vcc
